# W_in GEMM K-loop LDS-DMA staging also rebalanced 4+4 per super-phase (vmcnt 8/4/8/4), on top of combined v23
# baseline (speedup 1.0000x reference)
;     __host__ __device__ bool next(int i, Unit& u) const { const int L = i * G + c; if (L >= nunits) return false; u.pm = pm; u.pn = L & 7; u.ko = (L >> 3) * klen; return true; }
; #define PG8_STAGE(bufoff, gbase, voff) do { _Pragma("unroll") for (int _i = 0; _i < 2; ++_i) \
;         __builtin_amdgcn_global_load_lds((const unsigned*)((const char*)(gbase) + (voff)[_i]), (PG8_LAS unsigned*)(lds + (bufoff) + ldsw + _i * 8192), 16, 0, 0); } while (0)
; #define PG8_LDA(dst, b, h) do { _Pragma("unroll") for (int m = 0; m < 4; ++m) _Pragma("unroll") for (int k = 0; k < 2; ++k) dst[m][k] = *(const PG8_LAS bf16x8*)(lds + PG8_SA(b, h) + aoff + m * 2048 + k * 1024); } while (0)
; #define PG8_LDB(dst, b, h) do { _Pragma("unroll") for (int n = 0; n < 2; ++n) _Pragma("unroll") for (int k = 0; k < 2; ++k) dst[n][k] = *(const PG8_LAS bf16x8*)(lds + PG8_SB(b, h) + boff + n * 2048 + k * 1024); } while (0)
; #define PG8_WAIT_V(n) asm volatile("s_waitcnt vmcnt(" #n ")" ::: "memory")
; template <class Epi, class Sched, bool ALIGN_EPI = false, bool SP2 = false>
; __device__ __forceinline__ void gemm_phase(PG8_LAS unsigned char* lds, const Gemm g, const Sched& S, const Epi& E) {
;     ...
;         const bool has_next = S.next(ui + 1, nxt);
;         const char* nA = has_next ? (const char*)g.A + (size_t)nxt.pm * tstep + (size_t)nxt.ko * 2 : cA; const char* nB = has_next ? (const char*)g.Bt + (size_t)nxt.pn * tstep + (size_t)nxt.ko * 2 : cB;
;         for (int t = 0; t < nt; t += 2) {
;             const bool last = (t == nt - 2);
;             const char* a1 = cA + (size_t)(t + 1) * kstep;
;             const char* a2 = last ? nA : cA + (size_t)(t + 2) * kstep; const char* b2 = last ? nB : cB + (size_t)(t + 2) * kstep;
;             const char* a3 = a2 + kstep; const char* b3 = b2 + kstep;
;             if (last && has_next) S.a_ready(nxt);
;             if constexpr (SP2) {
;             PG8_LDB(B0, 0, 0); PG8_LDB(B1, 0, 1); PG8_SCHED; PG8_LDA(At, 0, 0); PG8_STAGE(PG8_SA(1, 1), a1 + hstep, voffA);
;             PG8_WAIT_V(8); PG8_WAIT_L(0); PG8_BAR; PG8_MMA(0, 0, At, B0); PG8_MMA(0, 1, At, B1); PG8_BAR; PG8_SCHED;
;     ...
;         for (int a = 0; a < 2; ++a)
; #pragma unroll
;             for (int b = 0; b < 2; ++b)
; #pragma unroll
;                 for (int m = 0; m < 4; ++m)
; #pragma unroll
;                     for (int n = 0; n < 2; ++n) acc[a][b][m][n] = (f32x4){0.f, 0.f, 0.f, 0.f};
.LBB0_148:
	s_ashr_i32 s17, s16, 31
	s_lshl_b64 s[18:19], s[16:17], 20
	s_add_u32 s18, s48, s18
	s_addc_u32 s19, s49, s19
	s_and_b64 s[20:21], s[6:7], exec
	s_cselect_b32 s1, s19, s23
	s_cselect_b32 s9, s18, s22
	s_ashr_i32 s15, s14, 31
	s_lshl_b64 s[20:21], s[14:15], 20
	s_add_u32 s20, s54, s20
	s_addc_u32 s21, s55, s21
	s_and_b64 s[30:31], s[6:7], exec
	s_cselect_b32 s15, s21, s27
	s_cselect_b32 s17, s20, s26
	v_lshl_add_u64 v[148:149], s[22:23], 0, v[128:129]
	v_lshl_add_u64 v[228:229], s[22:23], 0, v[130:131]
	s_add_u32 s22, s22, 0x80080
	s_addc_u32 s23, s23, 0
	s_add_u32 s30, s26, 0x100
	v_mov_b32_e32 v0, 0
	s_addc_u32 s31, s27, 0
	s_mov_b32 s56, -2
	v_mov_b32_e32 v1, v0
	v_mov_b32_e32 v2, v0
	v_mov_b32_e32 v3, v0
	v_mov_b32_e32 v4, v0
	v_mov_b32_e32 v5, v0
	v_mov_b32_e32 v6, v0
	v_mov_b32_e32 v7, v0
	v_mov_b32_e32 v16, v0
	v_mov_b32_e32 v17, v0
	v_mov_b32_e32 v18, v0
	v_mov_b32_e32 v19, v0
	v_mov_b32_e32 v20, v0
	v_mov_b32_e32 v21, v0
	v_mov_b32_e32 v22, v0
	v_mov_b32_e32 v23, v0
	v_mov_b32_e32 v32, v0
	v_mov_b32_e32 v33, v0
	v_mov_b32_e32 v34, v0
	v_mov_b32_e32 v35, v0
	v_mov_b32_e32 v36, v0
	v_mov_b32_e32 v37, v0
	v_mov_b32_e32 v38, v0
	v_mov_b32_e32 v39, v0
	v_mov_b32_e32 v48, v0
	v_mov_b32_e32 v49, v0
	v_mov_b32_e32 v50, v0
	v_mov_b32_e32 v51, v0
	v_mov_b32_e32 v52, v0
	v_mov_b32_e32 v53, v0
	v_mov_b32_e32 v54, v0
	v_mov_b32_e32 v55, v0
	v_mov_b32_e32 v8, v0
	v_mov_b32_e32 v9, v0
	v_mov_b32_e32 v10, v0
	v_mov_b32_e32 v11, v0
	v_mov_b32_e32 v12, v0
	v_mov_b32_e32 v13, v0
	v_mov_b32_e32 v14, v0
	v_mov_b32_e32 v15, v0
	v_mov_b32_e32 v24, v0
	v_mov_b32_e32 v25, v0
	v_mov_b32_e32 v26, v0
	v_mov_b32_e32 v27, v0
	v_mov_b32_e32 v28, v0
	v_mov_b32_e32 v29, v0
	v_mov_b32_e32 v30, v0
	v_mov_b32_e32 v31, v0
	v_mov_b32_e32 v40, v0
	v_mov_b32_e32 v41, v0
	v_mov_b32_e32 v42, v0
	v_mov_b32_e32 v43, v0
	v_mov_b32_e32 v44, v0
	v_mov_b32_e32 v45, v0
	v_mov_b32_e32 v46, v0
	v_mov_b32_e32 v47, v0
	v_mov_b32_e32 v56, v0
	v_mov_b32_e32 v57, v0
	v_mov_b32_e32 v58, v0
	v_mov_b32_e32 v59, v0
	v_mov_b32_e32 v60, v0
	v_mov_b32_e32 v61, v0
	v_mov_b32_e32 v62, v0
	v_mov_b32_e32 v63, v0
	v_mov_b32_e32 v64, v0
	v_mov_b32_e32 v65, v0
	v_mov_b32_e32 v66, v0
	v_mov_b32_e32 v67, v0
	v_mov_b32_e32 v68, v0
	v_mov_b32_e32 v69, v0
	v_mov_b32_e32 v70, v0
	v_mov_b32_e32 v71, v0
	v_mov_b32_e32 v80, v0
	v_mov_b32_e32 v81, v0
	v_mov_b32_e32 v82, v0
	v_mov_b32_e32 v83, v0
	v_mov_b32_e32 v84, v0
	v_mov_b32_e32 v85, v0
	v_mov_b32_e32 v86, v0
	v_mov_b32_e32 v87, v0
	v_mov_b32_e32 v96, v0
	v_mov_b32_e32 v97, v0
	v_mov_b32_e32 v98, v0
	v_mov_b32_e32 v99, v0
	v_mov_b32_e32 v100, v0
	v_mov_b32_e32 v101, v0
	v_mov_b32_e32 v102, v0
	v_mov_b32_e32 v103, v0
	v_mov_b32_e32 v112, v0
	v_mov_b32_e32 v113, v0
	v_mov_b32_e32 v114, v0
	v_mov_b32_e32 v115, v0
	v_mov_b32_e32 v116, v0
	v_mov_b32_e32 v117, v0
	v_mov_b32_e32 v118, v0
	v_mov_b32_e32 v119, v0
	v_mov_b32_e32 v72, v0
	v_mov_b32_e32 v73, v0
	v_mov_b32_e32 v74, v0
	v_mov_b32_e32 v75, v0
	v_mov_b32_e32 v76, v0
	v_mov_b32_e32 v77, v0
	v_mov_b32_e32 v78, v0
	v_mov_b32_e32 v79, v0
	v_mov_b32_e32 v88, v0
	v_mov_b32_e32 v89, v0
	v_mov_b32_e32 v90, v0
	v_mov_b32_e32 v91, v0
	v_mov_b32_e32 v92, v0
	v_mov_b32_e32 v93, v0
	v_mov_b32_e32 v94, v0
	v_mov_b32_e32 v95, v0
	v_mov_b32_e32 v104, v0
	v_mov_b32_e32 v105, v0
	v_mov_b32_e32 v106, v0
	v_mov_b32_e32 v107, v0
	v_mov_b32_e32 v108, v0
	v_mov_b32_e32 v109, v0
	v_mov_b32_e32 v110, v0
	v_mov_b32_e32 v111, v0
	v_mov_b32_e32 v120, v0
	v_mov_b32_e32 v121, v0
	v_mov_b32_e32 v122, v0
	v_mov_b32_e32 v123, v0
	v_mov_b32_e32 v124, v0
	v_mov_b32_e32 v125, v0
	v_mov_b32_e32 v126, v0
	v_mov_b32_e32 v127, v0
.LBB0_149:
	s_add_u32 s26, s22, 0xfff80080
	s_addc_u32 s27, s23, -1
	s_add_i32 s61, 0, 0x10000
	s_cmp_eq_u32 s56, 28
	s_cselect_b32 s37, s1, s27
	s_cselect_b32 s36, s9, s26
	v_add_u32_e32 v138, s61, v151
	s_cselect_b32 s27, s15, s31
	s_cselect_b32 s26, s17, s30
	s_add_i32 s76, 0, 0x14000
	ds_read_b128 v[154:157], v138
	ds_read_b128 v[160:163], v138 offset:1024
	ds_read_b128 v[164:167], v138 offset:2048
	ds_read_b128 v[168:171], v138 offset:3072
	v_add_u32_e32 v138, s76, v151
	ds_read_b128 v[172:175], v138
	ds_read_b128 v[176:179], v138 offset:1024
	ds_read_b128 v[180:183], v138 offset:2048
	ds_read_b128 v[184:187], v138 offset:3072
	v_lshl_add_u64 v[138:139], s[22:23], 0, v[134:135]
	s_add_i32 m0, s62, 0xc000
	ds_read_b128 v[188:191], v158
	ds_read_b128 v[192:195], v158 offset:1024
	ds_read_b128 v[196:199], v158 offset:2048
	ds_read_b128 v[208:211], v158 offset:3072
	ds_read_b128 v[212:215], v158 offset:4096
	ds_read_b128 v[216:219], v158 offset:5120
	ds_read_b128 v[220:223], v158 offset:6144
	ds_read_b128 v[224:227], v158 offset:7168
	global_load_lds_dwordx4 v[138:139], off
	v_lshl_add_u64 v[138:139], s[22:23], 0, v[136:137]
	s_add_i32 m0, s62, 0xe000
	s_nop 0
	global_load_lds_dwordx4 v[138:139], off
	v_lshl_add_u64 v[138:139], v[148:149], 0, s[84:85]
	s_mov_b32 m0, s67
	s_nop 0
	global_load_lds_dwordx4 v[138:139], off
	v_lshl_add_u64 v[138:139], v[228:229], 0, s[84:85]
	s_mov_b32 m0, s70
	s_nop 0
	global_load_lds_dwordx4 v[138:139], off
	s_waitcnt vmcnt(8)
	s_waitcnt lgkmcnt(0)
	s_barrier
; #define PG8_STAGE(bufoff, gbase, voff) do { _Pragma("unroll") for (int _i = 0; _i < 2; ++_i) \
;         __builtin_amdgcn_global_load_lds((const unsigned*)((const char*)(gbase) + (voff)[_i]), (PG8_LAS unsigned*)(lds + (bufoff) + ldsw + _i * 8192), 16, 0, 0); } while (0)
; #define PG8_LDA(dst, b, h) do { _Pragma("unroll") for (int m = 0; m < 4; ++m) _Pragma("unroll") for (int k = 0; k < 2; ++k) dst[m][k] = *(const PG8_LAS bf16x8*)(lds + PG8_SA(b, h) + aoff + m * 2048 + k * 1024); } while (0)
; #define PG8_LDB(dst, b, h) do { _Pragma("unroll") for (int n = 0; n < 2; ++n) _Pragma("unroll") for (int k = 0; k < 2; ++k) dst[n][k] = *(const PG8_LAS bf16x8*)(lds + PG8_SB(b, h) + boff + n * 2048 + k * 1024); } while (0)
; #define PG8_MMA(ai, bj, At, Bt) do { __builtin_amdgcn_s_setprio(1); _Pragma("unroll") for (int m = 0; m < 4; ++m) _Pragma("unroll") for (int n = 0; n < 2; ++n) _Pragma("unroll") for (int k = 0; k < 2; ++k) \
;         acc[ai][bj][m][n] = __builtin_amdgcn_mfma_f32_16x16x32_bf16(Bt[n][k], At[m][k], acc[ai][bj][m][n], 0, 0, 0); __builtin_amdgcn_s_setprio(0); } while (0)
; #define PG8_WAIT_V(n) asm volatile("s_waitcnt vmcnt(" #n ")" ::: "memory")
; #define PG8_WAIT_L(n) asm volatile("s_waitcnt lgkmcnt(" #n ")" ::: "memory")
; #define PG8_BAR __builtin_amdgcn_s_barrier()
; #define PG8_SCHED __builtin_amdgcn_sched_barrier(0)
; template <class Epi, class Sched, bool ALIGN_EPI = false, bool SP2 = false>
; __device__ __forceinline__ void gemm_phase(PG8_LAS unsigned char* lds, const Gemm g, const Sched& S, const Epi& E) {
;     ...
;             PG8_LDB(B0, 0, 0); PG8_LDB(B1, 0, 1); PG8_SCHED; PG8_LDA(At, 0, 0); PG8_STAGE(PG8_SA(1, 1), a1 + hstep, voffA);
;             PG8_WAIT_V(8); PG8_WAIT_L(0); PG8_BAR; PG8_MMA(0, 0, At, B0); PG8_MMA(0, 1, At, B1); PG8_BAR; PG8_SCHED;
;             PG8_LDA(At, 0, 1); PG8_STAGE(PG8_SB(0, 0), b2, voffB); PG8_STAGE(PG8_SB(0, 1), b2 + hstep, voffB); PG8_STAGE(PG8_SA(0, 0), a2, voffA);
;             PG8_WAIT_V(8); PG8_WAIT_L(0); PG8_BAR; PG8_MMA(1, 0, At, B0); PG8_MMA(1, 1, At, B1); PG8_BAR; PG8_SCHED;
	s_setprio 1
	s_waitcnt lgkmcnt(0)
	v_mfma_f32_16x16x32_bf16 v[124:127], v[154:157], v[188:191], v[124:127]
	v_mfma_f32_16x16x32_bf16 v[120:123], v[164:167], v[188:191], v[120:123]
	v_mfma_f32_16x16x32_bf16 v[108:111], v[154:157], v[196:199], v[108:111]
	v_mfma_f32_16x16x32_bf16 v[104:107], v[164:167], v[196:199], v[104:107]
	v_mfma_f32_16x16x32_bf16 v[92:95], v[154:157], v[212:215], v[92:95]
	v_mfma_f32_16x16x32_bf16 v[88:91], v[164:167], v[212:215], v[88:91]
	v_mfma_f32_16x16x32_bf16 v[76:79], v[154:157], v[220:223], v[76:79]
	v_mfma_f32_16x16x32_bf16 v[72:75], v[164:167], v[220:223], v[72:75]
	v_mfma_f32_16x16x32_bf16 v[124:127], v[160:163], v[192:195], v[124:127]
	v_mfma_f32_16x16x32_bf16 v[120:123], v[168:171], v[192:195], v[120:123]
	v_mfma_f32_16x16x32_bf16 v[108:111], v[160:163], v[208:211], v[108:111]
	v_mfma_f32_16x16x32_bf16 v[104:107], v[168:171], v[208:211], v[104:107]
	v_mfma_f32_16x16x32_bf16 v[92:95], v[160:163], v[216:219], v[92:95]
	v_mfma_f32_16x16x32_bf16 v[88:91], v[168:171], v[216:219], v[88:91]
	v_mfma_f32_16x16x32_bf16 v[76:79], v[160:163], v[224:227], v[76:79]
	v_mfma_f32_16x16x32_bf16 v[72:75], v[168:171], v[224:227], v[72:75]
	s_setprio 0
	s_setprio 1
	v_mfma_f32_16x16x32_bf16 v[116:119], v[172:175], v[188:191], v[116:119]
	v_mfma_f32_16x16x32_bf16 v[112:115], v[180:183], v[188:191], v[112:115]
	v_mfma_f32_16x16x32_bf16 v[100:103], v[172:175], v[196:199], v[100:103]
	v_mfma_f32_16x16x32_bf16 v[96:99], v[180:183], v[196:199], v[96:99]
	v_mfma_f32_16x16x32_bf16 v[84:87], v[172:175], v[212:215], v[84:87]
	v_mfma_f32_16x16x32_bf16 v[80:83], v[180:183], v[212:215], v[80:83]
	v_mfma_f32_16x16x32_bf16 v[68:71], v[172:175], v[220:223], v[68:71]
	v_mfma_f32_16x16x32_bf16 v[64:67], v[180:183], v[220:223], v[64:67]
	v_mfma_f32_16x16x32_bf16 v[116:119], v[176:179], v[192:195], v[116:119]
	v_mfma_f32_16x16x32_bf16 v[112:115], v[184:187], v[192:195], v[112:115]
	v_mfma_f32_16x16x32_bf16 v[100:103], v[176:179], v[208:211], v[100:103]
	v_mfma_f32_16x16x32_bf16 v[96:99], v[184:187], v[208:211], v[96:99]
	v_mfma_f32_16x16x32_bf16 v[84:87], v[176:179], v[216:219], v[84:87]
	v_mfma_f32_16x16x32_bf16 v[80:83], v[184:187], v[216:219], v[80:83]
	v_mfma_f32_16x16x32_bf16 v[68:71], v[176:179], v[224:227], v[68:71]
	v_mfma_f32_16x16x32_bf16 v[64:67], v[184:187], v[224:227], v[64:67]
	s_setprio 0
	s_barrier
	s_add_i32 s61, s61, s57
	v_lshl_add_u64 v[138:139], s[26:27], 0, v[140:141]
	s_mov_b32 m0, s61
	ds_read_b128 v[188:191], v158 offset:16384
	ds_read_b128 v[192:195], v158 offset:17408
	ds_read_b128 v[196:199], v158 offset:18432
	ds_read_b128 v[208:211], v158 offset:19456
	ds_read_b128 v[212:215], v158 offset:20480
	ds_read_b128 v[216:219], v158 offset:21504
	ds_read_b128 v[220:223], v158 offset:22528
	ds_read_b128 v[224:227], v158 offset:23552
	global_load_lds_dwordx4 v[138:139], off
	s_add_i32 m0, s61, 0x2000
	s_add_u32 s72, s26, 0x80000
	v_lshl_add_u64 v[146:147], s[26:27], 0, v[132:133]
	s_addc_u32 s73, s27, 0
	s_add_i32 s61, s76, s57
	global_load_lds_dwordx4 v[146:147], off
	v_lshl_add_u64 v[148:149], s[72:73], 0, v[140:141]
	s_mov_b32 m0, s61
	global_load_lds_dwordx4 v[148:149], off
	v_lshl_add_u64 v[148:149], s[72:73], 0, v[132:133]
	s_add_i32 m0, s61, 0x2000
	s_nop 0
	global_load_lds_dwordx4 v[148:149], off
	s_waitcnt vmcnt(4)
	s_waitcnt lgkmcnt(0)
	s_barrier
	s_setprio 1
	s_waitcnt lgkmcnt(0)
	v_mfma_f32_16x16x32_bf16 v[60:63], v[154:157], v[188:191], v[60:63]
	v_mfma_f32_16x16x32_bf16 v[56:59], v[164:167], v[188:191], v[56:59]
	v_mfma_f32_16x16x32_bf16 v[44:47], v[154:157], v[196:199], v[44:47]
	v_mfma_f32_16x16x32_bf16 v[40:43], v[164:167], v[196:199], v[40:43]
	v_mfma_f32_16x16x32_bf16 v[28:31], v[154:157], v[212:215], v[28:31]
	v_mfma_f32_16x16x32_bf16 v[24:27], v[164:167], v[212:215], v[24:27]
	v_mfma_f32_16x16x32_bf16 v[12:15], v[154:157], v[220:223], v[12:15]
	v_mfma_f32_16x16x32_bf16 v[8:11], v[164:167], v[220:223], v[8:11]
	v_mfma_f32_16x16x32_bf16 v[60:63], v[160:163], v[192:195], v[60:63]
	v_mfma_f32_16x16x32_bf16 v[56:59], v[168:171], v[192:195], v[56:59]
	v_mfma_f32_16x16x32_bf16 v[44:47], v[160:163], v[208:211], v[44:47]
	v_mfma_f32_16x16x32_bf16 v[40:43], v[168:171], v[208:211], v[40:43]
	v_mfma_f32_16x16x32_bf16 v[28:31], v[160:163], v[216:219], v[28:31]
	v_mfma_f32_16x16x32_bf16 v[24:27], v[168:171], v[216:219], v[24:27]
	v_mfma_f32_16x16x32_bf16 v[12:15], v[160:163], v[224:227], v[12:15]
	v_mfma_f32_16x16x32_bf16 v[8:11], v[168:171], v[224:227], v[8:11]
	s_setprio 0
	s_setprio 1
	v_mfma_f32_16x16x32_bf16 v[52:55], v[172:175], v[188:191], v[52:55]
	v_mfma_f32_16x16x32_bf16 v[48:51], v[180:183], v[188:191], v[48:51]
	v_mfma_f32_16x16x32_bf16 v[36:39], v[172:175], v[196:199], v[36:39]
	v_mfma_f32_16x16x32_bf16 v[32:35], v[180:183], v[196:199], v[32:35]
	v_mfma_f32_16x16x32_bf16 v[20:23], v[172:175], v[212:215], v[20:23]
	v_mfma_f32_16x16x32_bf16 v[16:19], v[180:183], v[212:215], v[16:19]
	v_mfma_f32_16x16x32_bf16 v[4:7], v[172:175], v[220:223], v[4:7]
	v_mfma_f32_16x16x32_bf16 v[0:3], v[180:183], v[220:223], v[0:3]
	v_mfma_f32_16x16x32_bf16 v[52:55], v[176:179], v[192:195], v[52:55]
	v_mfma_f32_16x16x32_bf16 v[48:51], v[184:187], v[192:195], v[48:51]
	v_mfma_f32_16x16x32_bf16 v[36:39], v[176:179], v[208:211], v[36:39]
	v_mfma_f32_16x16x32_bf16 v[32:35], v[184:187], v[208:211], v[32:35]
	v_mfma_f32_16x16x32_bf16 v[20:23], v[176:179], v[216:219], v[20:23]
	v_mfma_f32_16x16x32_bf16 v[16:19], v[184:187], v[216:219], v[16:19]
	v_mfma_f32_16x16x32_bf16 v[4:7], v[176:179], v[224:227], v[4:7]
	v_mfma_f32_16x16x32_bf16 v[0:3], v[184:187], v[224:227], v[0:3]
	s_setprio 0
	s_barrier
; #define PG8_STAGE(bufoff, gbase, voff) do { _Pragma("unroll") for (int _i = 0; _i < 2; ++_i) \
;         __builtin_amdgcn_global_load_lds((const unsigned*)((const char*)(gbase) + (voff)[_i]), (PG8_LAS unsigned*)(lds + (bufoff) + ldsw + _i * 8192), 16, 0, 0); } while (0)
; #define PG8_LDA(dst, b, h) do { _Pragma("unroll") for (int m = 0; m < 4; ++m) _Pragma("unroll") for (int k = 0; k < 2; ++k) dst[m][k] = *(const PG8_LAS bf16x8*)(lds + PG8_SA(b, h) + aoff + m * 2048 + k * 1024); } while (0)
; #define PG8_LDB(dst, b, h) do { _Pragma("unroll") for (int n = 0; n < 2; ++n) _Pragma("unroll") for (int k = 0; k < 2; ++k) dst[n][k] = *(const PG8_LAS bf16x8*)(lds + PG8_SB(b, h) + boff + n * 2048 + k * 1024); } while (0)
; #define PG8_MMA(ai, bj, At, Bt) do { __builtin_amdgcn_s_setprio(1); _Pragma("unroll") for (int m = 0; m < 4; ++m) _Pragma("unroll") for (int n = 0; n < 2; ++n) _Pragma("unroll") for (int k = 0; k < 2; ++k) \
;         acc[ai][bj][m][n] = __builtin_amdgcn_mfma_f32_16x16x32_bf16(Bt[n][k], At[m][k], acc[ai][bj][m][n], 0, 0, 0); __builtin_amdgcn_s_setprio(0); } while (0)
; #define PG8_WAIT_V(n) asm volatile("s_waitcnt vmcnt(" #n ")" ::: "memory")
; #define PG8_WAIT_L(n) asm volatile("s_waitcnt lgkmcnt(" #n ")" ::: "memory")
; #define PG8_BAR __builtin_amdgcn_s_barrier()
; #define PG8_SCHED __builtin_amdgcn_sched_barrier(0)
; template <class Epi, class Sched, bool ALIGN_EPI = false, bool SP2 = false>
; __device__ __forceinline__ void gemm_phase(PG8_LAS unsigned char* lds, const Gemm g, const Sched& S, const Epi& E) {
;     ...
;             PG8_LDB(B0, 1, 0); PG8_LDB(B1, 1, 1); PG8_SCHED; PG8_LDA(At, 1, 0); PG8_STAGE(PG8_SA(0, 1), a2 + hstep, voffA);
;             PG8_WAIT_V(8); PG8_WAIT_L(0); PG8_BAR; PG8_MMA(0, 0, At, B0); PG8_MMA(0, 1, At, B1); PG8_BAR; PG8_SCHED;
	s_add_i32 s61, 0, 0x18000
	v_add_u32_e32 v159, s61, v151
	s_add_i32 s72, 0, 0x1c000
	ds_read_b128 v[154:157], v159
	ds_read_b128 v[160:163], v159 offset:1024
	ds_read_b128 v[164:167], v159 offset:2048
	ds_read_b128 v[168:171], v159 offset:3072
	v_add_u32_e32 v159, s72, v151
	ds_read_b128 v[172:175], v159
	ds_read_b128 v[176:179], v159 offset:1024
	ds_read_b128 v[180:183], v159 offset:2048
	ds_read_b128 v[184:187], v159 offset:3072
	v_lshl_add_u64 v[148:149], s[36:37], 0, v[128:129]
	s_mov_b32 m0, s62
	s_nop 0
	global_load_lds_dwordx4 v[148:149], off
	v_lshl_add_u64 v[228:229], s[36:37], 0, v[130:131]
	s_mov_b32 m0, s63
	s_nop 0
	global_load_lds_dwordx4 v[228:229], off
	s_add_u32 s36, s36, 0x80000
	s_addc_u32 s37, s37, 0
	s_mov_b32 m0, s64
	v_lshl_add_u64 v[230:231], s[36:37], 0, v[128:129]
	ds_read_b128 v[188:191], v158 offset:32768
	ds_read_b128 v[192:195], v158 offset:33792
	ds_read_b128 v[196:199], v158 offset:34816
	ds_read_b128 v[208:211], v158 offset:35840
	ds_read_b128 v[212:215], v158 offset:36864
	ds_read_b128 v[216:219], v158 offset:37888
	ds_read_b128 v[220:223], v158 offset:38912
	ds_read_b128 v[224:227], v158 offset:39936
	global_load_lds_dwordx4 v[230:231], off
	v_lshl_add_u64 v[230:231], s[36:37], 0, v[130:131]
	s_mov_b32 m0, s65
	s_nop 0
	global_load_lds_dwordx4 v[230:231], off
	s_waitcnt vmcnt(8)
	s_waitcnt lgkmcnt(0)
	s_barrier
	s_setprio 1
	s_waitcnt lgkmcnt(0)
	v_mfma_f32_16x16x32_bf16 v[124:127], v[154:157], v[188:191], v[124:127]
	v_mfma_f32_16x16x32_bf16 v[120:123], v[164:167], v[188:191], v[120:123]
	v_mfma_f32_16x16x32_bf16 v[108:111], v[154:157], v[196:199], v[108:111]
	v_mfma_f32_16x16x32_bf16 v[104:107], v[164:167], v[196:199], v[104:107]
	v_mfma_f32_16x16x32_bf16 v[92:95], v[154:157], v[212:215], v[92:95]
	v_mfma_f32_16x16x32_bf16 v[88:91], v[164:167], v[212:215], v[88:91]
	v_mfma_f32_16x16x32_bf16 v[76:79], v[154:157], v[220:223], v[76:79]
	v_mfma_f32_16x16x32_bf16 v[72:75], v[164:167], v[220:223], v[72:75]
	v_mfma_f32_16x16x32_bf16 v[124:127], v[160:163], v[192:195], v[124:127]
	v_mfma_f32_16x16x32_bf16 v[120:123], v[168:171], v[192:195], v[120:123]
	v_mfma_f32_16x16x32_bf16 v[108:111], v[160:163], v[208:211], v[108:111]
	v_mfma_f32_16x16x32_bf16 v[104:107], v[168:171], v[208:211], v[104:107]
	v_mfma_f32_16x16x32_bf16 v[92:95], v[160:163], v[216:219], v[92:95]
	v_mfma_f32_16x16x32_bf16 v[88:91], v[168:171], v[216:219], v[88:91]
	v_mfma_f32_16x16x32_bf16 v[76:79], v[160:163], v[224:227], v[76:79]
	v_mfma_f32_16x16x32_bf16 v[72:75], v[168:171], v[224:227], v[72:75]
	s_setprio 0
	s_setprio 1
	v_mfma_f32_16x16x32_bf16 v[116:119], v[172:175], v[188:191], v[116:119]
	v_mfma_f32_16x16x32_bf16 v[112:115], v[180:183], v[188:191], v[112:115]
	v_mfma_f32_16x16x32_bf16 v[100:103], v[172:175], v[196:199], v[100:103]
	v_mfma_f32_16x16x32_bf16 v[96:99], v[180:183], v[196:199], v[96:99]
	v_mfma_f32_16x16x32_bf16 v[84:87], v[172:175], v[212:215], v[84:87]
	v_mfma_f32_16x16x32_bf16 v[80:83], v[180:183], v[212:215], v[80:83]
	v_mfma_f32_16x16x32_bf16 v[68:71], v[172:175], v[220:223], v[68:71]
	v_mfma_f32_16x16x32_bf16 v[64:67], v[180:183], v[220:223], v[64:67]
	v_mfma_f32_16x16x32_bf16 v[116:119], v[176:179], v[192:195], v[116:119]
	v_mfma_f32_16x16x32_bf16 v[112:115], v[184:187], v[192:195], v[112:115]
	v_mfma_f32_16x16x32_bf16 v[100:103], v[176:179], v[208:211], v[100:103]
	v_mfma_f32_16x16x32_bf16 v[96:99], v[184:187], v[208:211], v[96:99]
	v_mfma_f32_16x16x32_bf16 v[84:87], v[176:179], v[216:219], v[84:87]
	v_mfma_f32_16x16x32_bf16 v[80:83], v[184:187], v[216:219], v[80:83]
	v_mfma_f32_16x16x32_bf16 v[68:71], v[176:179], v[224:227], v[68:71]
	v_mfma_f32_16x16x32_bf16 v[64:67], v[184:187], v[224:227], v[64:67]
	s_setprio 0
	s_barrier
; #define PG8_STAGE(bufoff, gbase, voff) do { _Pragma("unroll") for (int _i = 0; _i < 2; ++_i) \
;         __builtin_amdgcn_global_load_lds((const unsigned*)((const char*)(gbase) + (voff)[_i]), (PG8_LAS unsigned*)(lds + (bufoff) + ldsw + _i * 8192), 16, 0, 0); } while (0)
; #define PG8_LDA(dst, b, h) do { _Pragma("unroll") for (int m = 0; m < 4; ++m) _Pragma("unroll") for (int k = 0; k < 2; ++k) dst[m][k] = *(const PG8_LAS bf16x8*)(lds + PG8_SA(b, h) + aoff + m * 2048 + k * 1024); } while (0)
; #define PG8_MMA(ai, bj, At, Bt) do { __builtin_amdgcn_s_setprio(1); _Pragma("unroll") for (int m = 0; m < 4; ++m) _Pragma("unroll") for (int n = 0; n < 2; ++n) _Pragma("unroll") for (int k = 0; k < 2; ++k) \
;         acc[ai][bj][m][n] = __builtin_amdgcn_mfma_f32_16x16x32_bf16(Bt[n][k], At[m][k], acc[ai][bj][m][n], 0, 0, 0); __builtin_amdgcn_s_setprio(0); } while (0)
; #define PG8_WAIT_V(n) asm volatile("s_waitcnt vmcnt(" #n ")" ::: "memory")
; #define PG8_WAIT_L(n) asm volatile("s_waitcnt lgkmcnt(" #n ")" ::: "memory")
; #define PG8_BAR __builtin_amdgcn_s_barrier()
; #define PG8_SCHED __builtin_amdgcn_sched_barrier(0)
; template <class Epi, class Sched, bool ALIGN_EPI = false, bool SP2 = false>
; __device__ __forceinline__ void gemm_phase(PG8_LAS unsigned char* lds, const Gemm g, const Sched& S, const Epi& E) {
;     ...
;         for (int t = 0; t < nt; t += 2) {
;     ...
;             PG8_LDA(At, 1, 1); PG8_STAGE(PG8_SB(1, 0), b3, voffB); PG8_STAGE(PG8_SB(1, 1), b3 + hstep, voffB); PG8_STAGE(PG8_SA(1, 0), a3, voffA);
;             PG8_WAIT_V(8); PG8_WAIT_L(0); PG8_BAR; PG8_MMA(1, 0, At, B0); PG8_MMA(1, 1, At, B1); PG8_BAR; PG8_SCHED;
	s_add_i32 s36, s61, s57
	v_lshl_add_u64 v[138:139], v[138:139], 0, s[84:85]
	s_mov_b32 m0, s36
	ds_read_b128 v[188:191], v158 offset:49152
	ds_read_b128 v[192:195], v158 offset:50176
	ds_read_b128 v[196:199], v158 offset:51200
	ds_read_b128 v[208:211], v158 offset:52224
	ds_read_b128 v[212:215], v158 offset:53248
	ds_read_b128 v[216:219], v158 offset:54272
	ds_read_b128 v[220:223], v158 offset:55296
	ds_read_b128 v[224:227], v158 offset:56320
	global_load_lds_dwordx4 v[138:139], off
	s_add_i32 m0, s36, 0x2000
	s_add_u32 s26, s26, 0x80080
	v_lshl_add_u64 v[138:139], v[146:147], 0, s[84:85]
	s_addc_u32 s27, s27, 0
	s_add_i32 s36, s72, s57
	global_load_lds_dwordx4 v[138:139], off
	v_lshl_add_u64 v[138:139], s[26:27], 0, v[140:141]
	s_mov_b32 m0, s36
	s_nop 0
	global_load_lds_dwordx4 v[138:139], off
	v_lshl_add_u64 v[138:139], s[26:27], 0, v[132:133]
	s_add_i32 m0, s36, 0x2000
	s_nop 0
	global_load_lds_dwordx4 v[138:139], off
	s_waitcnt vmcnt(4)
	s_waitcnt lgkmcnt(0)
	s_barrier
	s_setprio 1
	s_waitcnt lgkmcnt(0)
	v_mfma_f32_16x16x32_bf16 v[60:63], v[154:157], v[188:191], v[60:63]
	v_mfma_f32_16x16x32_bf16 v[56:59], v[164:167], v[188:191], v[56:59]
	v_mfma_f32_16x16x32_bf16 v[44:47], v[154:157], v[196:199], v[44:47]
	v_mfma_f32_16x16x32_bf16 v[40:43], v[164:167], v[196:199], v[40:43]
	v_mfma_f32_16x16x32_bf16 v[28:31], v[154:157], v[212:215], v[28:31]
	v_mfma_f32_16x16x32_bf16 v[24:27], v[164:167], v[212:215], v[24:27]
	v_mfma_f32_16x16x32_bf16 v[12:15], v[154:157], v[220:223], v[12:15]
	v_mfma_f32_16x16x32_bf16 v[8:11], v[164:167], v[220:223], v[8:11]
	v_mfma_f32_16x16x32_bf16 v[60:63], v[160:163], v[192:195], v[60:63]
	v_mfma_f32_16x16x32_bf16 v[56:59], v[168:171], v[192:195], v[56:59]
	v_mfma_f32_16x16x32_bf16 v[44:47], v[160:163], v[208:211], v[44:47]
	v_mfma_f32_16x16x32_bf16 v[40:43], v[168:171], v[208:211], v[40:43]
	v_mfma_f32_16x16x32_bf16 v[28:31], v[160:163], v[216:219], v[28:31]
	v_mfma_f32_16x16x32_bf16 v[24:27], v[168:171], v[216:219], v[24:27]
	v_mfma_f32_16x16x32_bf16 v[12:15], v[160:163], v[224:227], v[12:15]
	v_mfma_f32_16x16x32_bf16 v[8:11], v[168:171], v[224:227], v[8:11]
	s_setprio 0
	s_setprio 1
	v_mfma_f32_16x16x32_bf16 v[52:55], v[172:175], v[188:191], v[52:55]
	v_mfma_f32_16x16x32_bf16 v[48:51], v[180:183], v[188:191], v[48:51]
	v_mfma_f32_16x16x32_bf16 v[36:39], v[172:175], v[196:199], v[36:39]
	v_mfma_f32_16x16x32_bf16 v[32:35], v[180:183], v[196:199], v[32:35]
	v_mfma_f32_16x16x32_bf16 v[20:23], v[172:175], v[212:215], v[20:23]
	v_mfma_f32_16x16x32_bf16 v[16:19], v[180:183], v[212:215], v[16:19]
	v_mfma_f32_16x16x32_bf16 v[4:7], v[172:175], v[220:223], v[4:7]
	v_mfma_f32_16x16x32_bf16 v[0:3], v[180:183], v[220:223], v[0:3]
	v_mfma_f32_16x16x32_bf16 v[52:55], v[176:179], v[192:195], v[52:55]
	v_mfma_f32_16x16x32_bf16 v[48:51], v[184:187], v[192:195], v[48:51]
	v_mfma_f32_16x16x32_bf16 v[36:39], v[176:179], v[208:211], v[36:39]
	v_mfma_f32_16x16x32_bf16 v[32:35], v[184:187], v[208:211], v[32:35]
	v_mfma_f32_16x16x32_bf16 v[20:23], v[176:179], v[216:219], v[20:23]
	v_mfma_f32_16x16x32_bf16 v[16:19], v[184:187], v[216:219], v[16:19]
	v_mfma_f32_16x16x32_bf16 v[4:7], v[176:179], v[224:227], v[4:7]
	v_mfma_f32_16x16x32_bf16 v[0:3], v[184:187], v[224:227], v[0:3]
	s_setprio 0
	s_barrier
	s_add_i32 s56, s56, 2
	s_add_u32 s22, s22, 0x100
	s_addc_u32 s23, s23, 0
	s_add_u32 s30, s30, 0x100
	s_addc_u32 s31, s31, 0
	s_cmp_gt_u32 s56, 29
	s_cbranch_scc0 .LBB0_149
	s_and_b64 vcc, exec, s[12:13]
	s_cbranch_vccz .LBB0_152
	s_barrier
